# speedup vs baseline: 1.0332x; 1.0001x over previous
; DI void attn_unit(unsigned char* smem, const bf16_t* __restrict__ proj, bf16_t* __restrict__ y, int bh, int qb) {
;     ...
;         {
;             const int done = __all(R < -160.f) ? 1 : 0;
;             wdone = done != 0;
;             if (lane == 0) flags[(kt & 1) * 8 + wid] = done;
;         }
.LBB0_203:
	s_or_b64 exec, exec, s[0:1]
	s_mov_b32 s0, 0xc3200000
	v_cmp_gt_f32_e32 vcc, s0, v94
	s_cmp_eq_u64 vcc, exec
	s_cselect_b64 s[52:53], -1, 0
	s_and_b32 s50, s58, 8
	s_and_saveexec_b64 s[0:1], s[6:7]
	s_cbranch_execz .LBB0_205
	s_lshl_b32 s51, s50, 2
	s_add_i32 s51, s56, s51
	s_mov_b64 s[62:63], src_shared_base
	s_add_i32 s51, s51, 0x8c00
	v_mov_b32_e32 v32, s51
	v_mov_b32_e32 v33, s63
	v_cndmask_b32_e64 v34, 0, 1, s[52:53]
	ds_write_b32 v32, v34
